# RG-LRU scan passes 1 and 2: all loads of an 8-token block issued back to back, consumed with counted waits (same arithmetic)
# speedup vs baseline: 1.0081x; 1.0081x over previous
.LBB0_1452:
	v_lshl_add_u64 v[34:35], s[0:1], 0, v[30:31]
	v_lshl_add_u64 v[52:53], s[0:1], 0, v[32:33]
	s_mov_b64 s[6:7], 0x2000
	v_lshl_add_u64 v[60:61], v[34:35], 0, s[10:11]
	v_lshl_add_u64 v[62:63], v[60:61], 0, s[6:7]
	v_lshl_add_u64 v[64:65], v[62:63], 0, s[6:7]
	v_lshl_add_u64 v[66:67], v[64:65], 0, s[6:7]
	s_mov_b64 s[6:7], 0x11000800
	v_lshl_add_u64 v[68:69], v[52:53], 0, s[6:7]
	s_mov_b64 s[6:7], 0x1800
	v_lshl_add_u64 v[70:71], v[68:69], 0, s[6:7]
	v_lshl_add_u64 v[72:73], v[70:71], 0, s[6:7]
	global_load_dwordx4 v[84:87], v[60:61], off offset:-4096
	global_load_dwordx4 v[88:91], v[60:61], off offset:-4080
	global_load_dwordx4 v[92:95], v[68:69], off offset:-2048
	global_load_dwordx4 v[96:99], v[60:61], off
	global_load_dwordx4 v[100:103], v[60:61], off offset:16
	global_load_dwordx4 v[104:107], v[68:69], off
	global_load_dwordx4 v[108:111], v[62:63], off offset:-4096
	global_load_dwordx4 v[112:115], v[62:63], off offset:-4080
	global_load_dwordx4 v[116:119], v[68:69], off offset:2048
	global_load_dwordx4 v[120:123], v[62:63], off
	global_load_dwordx4 v[124:127], v[62:63], off offset:16
	global_load_dwordx4 v[128:131], v[70:71], off offset:-2048
	global_load_dwordx4 v[132:135], v[64:65], off offset:-4096
	global_load_dwordx4 v[136:139], v[64:65], off offset:-4080
	global_load_dwordx4 v[140:143], v[70:71], off
	global_load_dwordx4 v[144:147], v[64:65], off
	global_load_dwordx4 v[148:151], v[64:65], off offset:16
	global_load_dwordx4 v[152:155], v[70:71], off offset:2048
	global_load_dwordx4 v[156:159], v[66:67], off offset:-4096
	global_load_dwordx4 v[160:163], v[66:67], off offset:-4080
	global_load_dwordx4 v[164:167], v[72:73], off offset:-2048
	global_load_dwordx4 v[168:171], v[66:67], off
	global_load_dwordx4 v[172:175], v[66:67], off offset:16
	global_load_dwordx4 v[176:179], v[72:73], off
	v_lshl_add_u64 v[32:33], v[32:33], 0, s[46:47]
	v_lshl_add_u64 v[30:31], v[30:31], 0, s[64:65]
	s_waitcnt vmcnt(21)
	v_lshlrev_b32_e32 v56, 16, v92
	v_and_b32_e32 v57, 0xffff0000, v92
	v_pk_fma_f32 v[8:9], v[84:85], v[8:9], v[56:57]
	v_pk_mul_f32 v[12:13], v[12:13], v[84:85]
	v_lshlrev_b32_e32 v58, 16, v93
	v_and_b32_e32 v59, 0xffff0000, v93
	v_pk_fma_f32 v[10:11], v[86:87], v[10:11], v[58:59]
	v_pk_mul_f32 v[14:15], v[14:15], v[86:87]
	v_lshlrev_b32_e32 v56, 16, v94
	v_and_b32_e32 v57, 0xffff0000, v94
	v_pk_fma_f32 v[0:1], v[88:89], v[0:1], v[56:57]
	v_pk_mul_f32 v[4:5], v[4:5], v[88:89]
	v_lshlrev_b32_e32 v58, 16, v95
	v_and_b32_e32 v59, 0xffff0000, v95
	v_pk_fma_f32 v[2:3], v[90:91], v[2:3], v[58:59]
	v_pk_mul_f32 v[6:7], v[6:7], v[90:91]
	s_waitcnt vmcnt(18)
	v_lshlrev_b32_e32 v56, 16, v104
	v_and_b32_e32 v57, 0xffff0000, v104
	v_pk_fma_f32 v[8:9], v[96:97], v[8:9], v[56:57]
	v_pk_mul_f32 v[12:13], v[12:13], v[96:97]
	v_lshlrev_b32_e32 v58, 16, v105
	v_and_b32_e32 v59, 0xffff0000, v105
	v_pk_fma_f32 v[10:11], v[98:99], v[10:11], v[58:59]
	v_pk_mul_f32 v[14:15], v[14:15], v[98:99]
	v_lshlrev_b32_e32 v56, 16, v106
	v_and_b32_e32 v57, 0xffff0000, v106
	v_pk_fma_f32 v[0:1], v[100:101], v[0:1], v[56:57]
	v_pk_mul_f32 v[4:5], v[4:5], v[100:101]
	v_lshlrev_b32_e32 v58, 16, v107
	v_and_b32_e32 v59, 0xffff0000, v107
	v_pk_fma_f32 v[2:3], v[102:103], v[2:3], v[58:59]
	v_pk_mul_f32 v[6:7], v[6:7], v[102:103]
	s_waitcnt vmcnt(15)
	v_lshlrev_b32_e32 v56, 16, v116
	v_and_b32_e32 v57, 0xffff0000, v116
	v_pk_fma_f32 v[8:9], v[108:109], v[8:9], v[56:57]
	v_pk_mul_f32 v[12:13], v[12:13], v[108:109]
	v_lshlrev_b32_e32 v58, 16, v117
	v_and_b32_e32 v59, 0xffff0000, v117
	v_pk_fma_f32 v[10:11], v[110:111], v[10:11], v[58:59]
	v_pk_mul_f32 v[14:15], v[14:15], v[110:111]
	v_lshlrev_b32_e32 v56, 16, v118
	v_and_b32_e32 v57, 0xffff0000, v118
	v_pk_fma_f32 v[0:1], v[112:113], v[0:1], v[56:57]
	v_pk_mul_f32 v[4:5], v[4:5], v[112:113]
	v_lshlrev_b32_e32 v58, 16, v119
	v_and_b32_e32 v59, 0xffff0000, v119
	v_pk_fma_f32 v[2:3], v[114:115], v[2:3], v[58:59]
	v_pk_mul_f32 v[6:7], v[6:7], v[114:115]
	s_waitcnt vmcnt(12)
	v_lshlrev_b32_e32 v56, 16, v128
	v_and_b32_e32 v57, 0xffff0000, v128
	v_pk_fma_f32 v[8:9], v[120:121], v[8:9], v[56:57]
	v_pk_mul_f32 v[12:13], v[12:13], v[120:121]
	v_lshlrev_b32_e32 v58, 16, v129
	v_and_b32_e32 v59, 0xffff0000, v129
	v_pk_fma_f32 v[10:11], v[122:123], v[10:11], v[58:59]
	v_pk_mul_f32 v[14:15], v[14:15], v[122:123]
	v_lshlrev_b32_e32 v56, 16, v130
	v_and_b32_e32 v57, 0xffff0000, v130
	v_pk_fma_f32 v[0:1], v[124:125], v[0:1], v[56:57]
	v_pk_mul_f32 v[4:5], v[4:5], v[124:125]
	v_lshlrev_b32_e32 v58, 16, v131
	v_and_b32_e32 v59, 0xffff0000, v131
	v_pk_fma_f32 v[2:3], v[126:127], v[2:3], v[58:59]
	v_pk_mul_f32 v[6:7], v[6:7], v[126:127]
	s_waitcnt vmcnt(9)
	v_lshlrev_b32_e32 v56, 16, v140
	v_and_b32_e32 v57, 0xffff0000, v140
	v_pk_fma_f32 v[8:9], v[132:133], v[8:9], v[56:57]
	v_pk_mul_f32 v[12:13], v[12:13], v[132:133]
	v_lshlrev_b32_e32 v58, 16, v141
	v_and_b32_e32 v59, 0xffff0000, v141
	v_pk_fma_f32 v[10:11], v[134:135], v[10:11], v[58:59]
	v_pk_mul_f32 v[14:15], v[14:15], v[134:135]
	v_lshlrev_b32_e32 v56, 16, v142
	v_and_b32_e32 v57, 0xffff0000, v142
	v_pk_fma_f32 v[0:1], v[136:137], v[0:1], v[56:57]
	v_pk_mul_f32 v[4:5], v[4:5], v[136:137]
	v_lshlrev_b32_e32 v58, 16, v143
	v_and_b32_e32 v59, 0xffff0000, v143
	v_pk_fma_f32 v[2:3], v[138:139], v[2:3], v[58:59]
	v_pk_mul_f32 v[6:7], v[6:7], v[138:139]
	s_waitcnt vmcnt(6)
	v_lshlrev_b32_e32 v56, 16, v152
	v_and_b32_e32 v57, 0xffff0000, v152
	v_pk_fma_f32 v[8:9], v[144:145], v[8:9], v[56:57]
	v_pk_mul_f32 v[12:13], v[12:13], v[144:145]
	v_lshlrev_b32_e32 v58, 16, v153
	v_and_b32_e32 v59, 0xffff0000, v153
	v_pk_fma_f32 v[10:11], v[146:147], v[10:11], v[58:59]
	v_pk_mul_f32 v[14:15], v[14:15], v[146:147]
	v_lshlrev_b32_e32 v56, 16, v154
	v_and_b32_e32 v57, 0xffff0000, v154
	v_pk_fma_f32 v[0:1], v[148:149], v[0:1], v[56:57]
	v_pk_mul_f32 v[4:5], v[4:5], v[148:149]
	v_lshlrev_b32_e32 v58, 16, v155
	v_and_b32_e32 v59, 0xffff0000, v155
	v_pk_fma_f32 v[2:3], v[150:151], v[2:3], v[58:59]
	v_pk_mul_f32 v[6:7], v[6:7], v[150:151]
	s_waitcnt vmcnt(3)
	v_lshlrev_b32_e32 v56, 16, v164
	v_and_b32_e32 v57, 0xffff0000, v164
	v_pk_fma_f32 v[8:9], v[156:157], v[8:9], v[56:57]
	v_pk_mul_f32 v[12:13], v[12:13], v[156:157]
	v_lshlrev_b32_e32 v58, 16, v165
	v_and_b32_e32 v59, 0xffff0000, v165
	v_pk_fma_f32 v[10:11], v[158:159], v[10:11], v[58:59]
	v_pk_mul_f32 v[14:15], v[14:15], v[158:159]
	v_lshlrev_b32_e32 v56, 16, v166
	v_and_b32_e32 v57, 0xffff0000, v166
	v_pk_fma_f32 v[0:1], v[160:161], v[0:1], v[56:57]
	v_pk_mul_f32 v[4:5], v[4:5], v[160:161]
	v_lshlrev_b32_e32 v58, 16, v167
	v_and_b32_e32 v59, 0xffff0000, v167
	v_pk_fma_f32 v[2:3], v[162:163], v[2:3], v[58:59]
	v_pk_mul_f32 v[6:7], v[6:7], v[162:163]
	s_waitcnt vmcnt(0)
	v_lshlrev_b32_e32 v56, 16, v176
	v_and_b32_e32 v57, 0xffff0000, v176
	v_pk_fma_f32 v[8:9], v[168:169], v[8:9], v[56:57]
	v_pk_mul_f32 v[12:13], v[12:13], v[168:169]
	v_lshlrev_b32_e32 v58, 16, v177
	v_and_b32_e32 v59, 0xffff0000, v177
	v_pk_fma_f32 v[10:11], v[170:171], v[10:11], v[58:59]
	v_pk_mul_f32 v[14:15], v[14:15], v[170:171]
	v_lshlrev_b32_e32 v56, 16, v178
	v_and_b32_e32 v57, 0xffff0000, v178
	v_pk_fma_f32 v[0:1], v[172:173], v[0:1], v[56:57]
	v_pk_mul_f32 v[4:5], v[4:5], v[172:173]
	v_lshlrev_b32_e32 v58, 16, v179
	v_and_b32_e32 v59, 0xffff0000, v179
	v_pk_fma_f32 v[2:3], v[174:175], v[2:3], v[58:59]
	v_pk_mul_f32 v[6:7], v[6:7], v[174:175]
	s_add_i32 s2, s2, -8
	s_cmp_eq_u32 s2, 0
	s_cbranch_scc0 .LBB0_1452
	s_ashr_i32 s9, s8, 31
	s_lshl_b64 s[6:7], s[8:9], 12
	v_lshl_add_u64 v[30:31], s[6:7], 0, v[16:17]
	v_lshlrev_b64 v[30:31], 2, v[30:31]
	v_lshl_add_u64 v[32:33], v[18:19], 0, v[30:31]
	v_lshl_add_u64 v[30:31], v[20:21], 0, v[30:31]
	global_store_dwordx4 v[32:33], v[12:15], off
	global_store_dwordx4 v[32:33], v[4:7], off offset:16
	global_store_dwordx4 v[30:31], v[8:11], off
	global_store_dwordx4 v[30:31], v[0:3], off offset:16
	ds_write_b128 v37, v[12:15]
	ds_write_b128 v37, v[8:11] offset:32
	ds_write_b128 v37, v[4:7] offset:16
	ds_write_b128 v37, v[0:3] offset:48
	s_waitcnt lgkmcnt(0)
	s_barrier
	s_and_saveexec_b64 s[2:3], vcc
	s_cbranch_execz .LBB0_1450
	ds_read_b128 v[30:33], v37 offset:8192
	ds_read_b128 v[38:41], v37 offset:8208
	ds_read_b128 v[42:45], v37 offset:8224
	ds_read_b128 v[46:49], v37 offset:8240
	ds_read_b128 v[50:53], v37 offset:16384
	ds_read_b128 v[54:57], v37 offset:16400
	ds_read_b128 v[58:61], v37 offset:24576
	ds_read_b128 v[62:65], v37 offset:24592
	ds_read_b128 v[66:69], v37 offset:16416
	ds_read_b128 v[70:73], v37 offset:16432
	ds_read_b128 v[74:77], v37 offset:24608
	ds_read_b128 v[78:81], v37 offset:24624
	s_waitcnt lgkmcnt(10)
	v_pk_mul_f32 v[4:5], v[38:39], v[4:5]
	v_pk_mul_f32 v[6:7], v[40:41], v[6:7]
	s_waitcnt lgkmcnt(6)
	v_pk_mul_f32 v[4:5], v[54:55], v[4:5]
	v_pk_mul_f32 v[6:7], v[56:57], v[6:7]
	v_lshl_add_u64 v[34:35], v[22:23], 0, s[6:7]
	s_waitcnt lgkmcnt(4)
	v_pk_mul_f32 v[4:5], v[62:63], v[4:5]
	v_pk_mul_f32 v[6:7], v[64:65], v[6:7]
	v_pk_mul_f32 v[12:13], v[30:31], v[12:13]
	v_pk_mul_f32 v[14:15], v[32:33], v[14:15]
	global_store_dwordx4 v[34:35], v[4:7], off offset:16
	v_pk_fma_f32 v[0:1], v[38:39], v[0:1], v[46:47]
	v_pk_fma_f32 v[2:3], v[40:41], v[2:3], v[48:49]
	v_pk_fma_f32 v[4:5], v[30:31], v[8:9], v[42:43]
	v_pk_fma_f32 v[6:7], v[32:33], v[10:11], v[44:45]
	v_pk_mul_f32 v[12:13], v[50:51], v[12:13]
	v_pk_mul_f32 v[14:15], v[52:53], v[14:15]
	s_waitcnt lgkmcnt(3)
	v_pk_fma_f32 v[4:5], v[50:51], v[4:5], v[66:67]
	v_pk_fma_f32 v[6:7], v[52:53], v[6:7], v[68:69]
	s_waitcnt lgkmcnt(2)
	v_pk_fma_f32 v[0:1], v[54:55], v[0:1], v[70:71]
	v_pk_fma_f32 v[2:3], v[56:57], v[2:3], v[72:73]
	v_lshl_add_u64 v[82:83], v[24:25], 0, s[6:7]
	v_pk_mul_f32 v[12:13], v[58:59], v[12:13]
	v_pk_mul_f32 v[14:15], v[60:61], v[14:15]
	s_waitcnt lgkmcnt(1)
	v_pk_fma_f32 v[4:5], v[58:59], v[4:5], v[74:75]
	v_pk_fma_f32 v[6:7], v[60:61], v[6:7], v[76:77]
	s_waitcnt lgkmcnt(0)
	v_pk_fma_f32 v[0:1], v[62:63], v[0:1], v[78:79]
	v_pk_fma_f32 v[2:3], v[64:65], v[2:3], v[80:81]
	global_store_dwordx4 v[34:35], v[12:15], off
	global_store_dwordx4 v[82:83], v[4:7], off
	global_store_dwordx4 v[82:83], v[0:3], off offset:16
	s_branch .LBB0_1450

.LBB0_1527:
	s_nop 0
	v_lshl_add_u64 v[12:13], s[0:1], 0, v[8:9]
	v_lshl_add_u64 v[14:15], s[0:1], 0, v[10:11]
	s_mov_b64 s[10:11], 0x2000
	v_lshl_add_u64 v[176:177], v[12:13], 0, s[8:9]
	v_lshl_add_u64 v[178:179], v[176:177], 0, s[10:11]
	v_lshl_add_u64 v[180:181], v[178:179], 0, s[10:11]
	v_lshl_add_u64 v[182:183], v[180:181], 0, s[10:11]
	global_load_dwordx4 v[80:83], v[176:177], off offset:-4096
	global_load_dwordx4 v[84:87], v[176:177], off offset:-4080
	global_load_dwordx4 v[96:99], v[176:177], off
	global_load_dwordx4 v[100:103], v[176:177], off offset:16
	global_load_dwordx4 v[112:115], v[178:179], off offset:-4096
	global_load_dwordx4 v[116:119], v[178:179], off offset:-4080
	global_load_dwordx4 v[128:131], v[178:179], off
	global_load_dwordx4 v[132:135], v[178:179], off offset:16
	global_load_dwordx4 v[144:147], v[180:181], off offset:-4096
	global_load_dwordx4 v[148:151], v[180:181], off offset:-4080
	global_load_dwordx4 v[160:163], v[180:181], off
	global_load_dwordx4 v[164:167], v[180:181], off offset:16
	global_load_dwordx4 v[32:35], v[182:183], off offset:-4096
	global_load_dwordx4 v[36:39], v[182:183], off offset:-4080
	global_load_dwordx4 v[60:63], v[182:183], off
	global_load_dwordx4 v[64:67], v[182:183], off offset:16
	s_mov_b64 s[10:11], 0x11000800
	v_lshl_add_u64 v[176:177], v[14:15], 0, s[10:11]
	s_mov_b64 s[10:11], 0x1800
	v_lshl_add_u64 v[178:179], v[176:177], 0, s[10:11]
	v_lshl_add_u64 v[180:181], v[178:179], 0, s[10:11]
	global_load_dwordx4 v[88:91], v[176:177], off offset:-2048
	global_load_dwordx4 v[104:107], v[176:177], off
	global_load_dwordx4 v[120:123], v[176:177], off offset:2048
	global_load_dwordx4 v[136:139], v[178:179], off offset:-2048
	global_load_dwordx4 v[152:155], v[178:179], off
	global_load_dwordx4 v[168:171], v[178:179], off offset:2048
	global_load_dwordx4 v[40:43], v[180:181], off offset:-2048
	global_load_dwordx4 v[68:71], v[180:181], off
	s_mov_b64 s[10:11], 0xd000800
	v_lshl_add_u64 v[176:177], v[14:15], 0, s[10:11]
	s_mov_b64 s[10:11], 0x1800
	v_lshl_add_u64 v[178:179], v[176:177], 0, s[10:11]
	v_lshl_add_u64 v[180:181], v[178:179], 0, s[10:11]
	global_load_dwordx4 v[92:95], v[176:177], off offset:-2048
	global_load_dwordx4 v[108:111], v[176:177], off
	global_load_dwordx4 v[124:127], v[176:177], off offset:2048
	global_load_dwordx4 v[140:143], v[178:179], off offset:-2048
	global_load_dwordx4 v[156:159], v[178:179], off
	global_load_dwordx4 v[172:175], v[178:179], off offset:2048
	global_load_dwordx4 v[44:47], v[180:181], off offset:-2048
	global_load_dwordx4 v[72:75], v[180:181], off
	s_mov_b64 s[10:11], 0x09000800
	v_lshl_add_u64 v[76:77], v[14:15], 0, s[10:11]
	s_mov_b64 s[10:11], 0x1800
	v_lshl_add_u64 v[78:79], v[76:77], 0, s[10:11]
	v_lshl_add_u64 v[28:29], v[78:79], 0, s[10:11]
	v_lshl_add_u64 v[10:11], v[10:11], 0, s[46:47]
	v_lshl_add_u64 v[8:9], v[8:9], 0, s[64:65]
	s_waitcnt vmcnt(7)
	v_lshlrev_b32_e32 v56, 16, v88
	v_and_b32_e32 v57, 0xffff0000, v88
	v_pk_fma_f32 v[30:31], v[30:31], v[80:81], v[56:57]
	v_lshlrev_b32_e32 v58, 16, v92
	v_and_b32_e32 v59, 0xffff0000, v92
	v_pk_mul_f32 v[58:59], v[30:31], v[58:59]
	v_cvt_pk_bf16_f32 v12, v58, v59
	v_lshlrev_b32_e32 v56, 16, v89
	v_and_b32_e32 v57, 0xffff0000, v89
	v_pk_fma_f32 v[4:5], v[4:5], v[82:83], v[56:57]
	v_lshlrev_b32_e32 v58, 16, v93
	v_and_b32_e32 v59, 0xffff0000, v93
	v_pk_mul_f32 v[58:59], v[4:5], v[58:59]
	v_cvt_pk_bf16_f32 v13, v58, v59
	v_lshlrev_b32_e32 v56, 16, v90
	v_and_b32_e32 v57, 0xffff0000, v90
	v_pk_fma_f32 v[6:7], v[6:7], v[84:85], v[56:57]
	v_lshlrev_b32_e32 v58, 16, v94
	v_and_b32_e32 v59, 0xffff0000, v94
	v_pk_mul_f32 v[58:59], v[6:7], v[58:59]
	v_cvt_pk_bf16_f32 v14, v58, v59
	v_lshlrev_b32_e32 v56, 16, v91
	v_and_b32_e32 v57, 0xffff0000, v91
	v_pk_fma_f32 v[0:1], v[0:1], v[86:87], v[56:57]
	v_lshlrev_b32_e32 v58, 16, v95
	v_and_b32_e32 v59, 0xffff0000, v95
	v_pk_mul_f32 v[58:59], v[0:1], v[58:59]
	v_cvt_pk_bf16_f32 v15, v58, v59
	global_store_dwordx4 v[76:77], v[12:15], off offset:-2048
	s_waitcnt vmcnt(6)
	v_lshlrev_b32_e32 v56, 16, v104
	v_and_b32_e32 v57, 0xffff0000, v104
	v_pk_fma_f32 v[30:31], v[30:31], v[96:97], v[56:57]
	v_lshlrev_b32_e32 v58, 16, v108
	v_and_b32_e32 v59, 0xffff0000, v108
	v_pk_mul_f32 v[58:59], v[30:31], v[58:59]
	v_cvt_pk_bf16_f32 v52, v58, v59
	v_lshlrev_b32_e32 v56, 16, v105
	v_and_b32_e32 v57, 0xffff0000, v105
	v_pk_fma_f32 v[4:5], v[4:5], v[98:99], v[56:57]
	v_lshlrev_b32_e32 v58, 16, v109
	v_and_b32_e32 v59, 0xffff0000, v109
	v_pk_mul_f32 v[58:59], v[4:5], v[58:59]
	v_cvt_pk_bf16_f32 v53, v58, v59
	v_lshlrev_b32_e32 v56, 16, v106
	v_and_b32_e32 v57, 0xffff0000, v106
	v_pk_fma_f32 v[6:7], v[6:7], v[100:101], v[56:57]
	v_lshlrev_b32_e32 v58, 16, v110
	v_and_b32_e32 v59, 0xffff0000, v110
	v_pk_mul_f32 v[58:59], v[6:7], v[58:59]
	v_cvt_pk_bf16_f32 v54, v58, v59
	v_lshlrev_b32_e32 v56, 16, v107
	v_and_b32_e32 v57, 0xffff0000, v107
	v_pk_fma_f32 v[0:1], v[0:1], v[102:103], v[56:57]
	v_lshlrev_b32_e32 v58, 16, v111
	v_and_b32_e32 v59, 0xffff0000, v111
	v_pk_mul_f32 v[58:59], v[0:1], v[58:59]
	v_cvt_pk_bf16_f32 v55, v58, v59
	global_store_dwordx4 v[76:77], v[52:55], off
	s_waitcnt vmcnt(5)
	v_lshlrev_b32_e32 v56, 16, v120
	v_and_b32_e32 v57, 0xffff0000, v120
	v_pk_fma_f32 v[30:31], v[30:31], v[112:113], v[56:57]
	v_lshlrev_b32_e32 v58, 16, v124
	v_and_b32_e32 v59, 0xffff0000, v124
	v_pk_mul_f32 v[58:59], v[30:31], v[58:59]
	v_cvt_pk_bf16_f32 v12, v58, v59
	v_lshlrev_b32_e32 v56, 16, v121
	v_and_b32_e32 v57, 0xffff0000, v121
	v_pk_fma_f32 v[4:5], v[4:5], v[114:115], v[56:57]
	v_lshlrev_b32_e32 v58, 16, v125
	v_and_b32_e32 v59, 0xffff0000, v125
	v_pk_mul_f32 v[58:59], v[4:5], v[58:59]
	v_cvt_pk_bf16_f32 v13, v58, v59
	v_lshlrev_b32_e32 v56, 16, v122
	v_and_b32_e32 v57, 0xffff0000, v122
	v_pk_fma_f32 v[6:7], v[6:7], v[116:117], v[56:57]
	v_lshlrev_b32_e32 v58, 16, v126
	v_and_b32_e32 v59, 0xffff0000, v126
	v_pk_mul_f32 v[58:59], v[6:7], v[58:59]
	v_cvt_pk_bf16_f32 v14, v58, v59
	v_lshlrev_b32_e32 v56, 16, v123
	v_and_b32_e32 v57, 0xffff0000, v123
	v_pk_fma_f32 v[0:1], v[0:1], v[118:119], v[56:57]
	v_lshlrev_b32_e32 v58, 16, v127
	v_and_b32_e32 v59, 0xffff0000, v127
	v_pk_mul_f32 v[58:59], v[0:1], v[58:59]
	v_cvt_pk_bf16_f32 v15, v58, v59
	global_store_dwordx4 v[76:77], v[12:15], off offset:2048
	s_waitcnt vmcnt(4)
	v_lshlrev_b32_e32 v56, 16, v136
	v_and_b32_e32 v57, 0xffff0000, v136
	v_pk_fma_f32 v[30:31], v[30:31], v[128:129], v[56:57]
	v_lshlrev_b32_e32 v58, 16, v140
	v_and_b32_e32 v59, 0xffff0000, v140
	v_pk_mul_f32 v[58:59], v[30:31], v[58:59]
	v_cvt_pk_bf16_f32 v52, v58, v59
	v_lshlrev_b32_e32 v56, 16, v137
	v_and_b32_e32 v57, 0xffff0000, v137
	v_pk_fma_f32 v[4:5], v[4:5], v[130:131], v[56:57]
	v_lshlrev_b32_e32 v58, 16, v141
	v_and_b32_e32 v59, 0xffff0000, v141
	v_pk_mul_f32 v[58:59], v[4:5], v[58:59]
	v_cvt_pk_bf16_f32 v53, v58, v59
	v_lshlrev_b32_e32 v56, 16, v138
	v_and_b32_e32 v57, 0xffff0000, v138
	v_pk_fma_f32 v[6:7], v[6:7], v[132:133], v[56:57]
	v_lshlrev_b32_e32 v58, 16, v142
	v_and_b32_e32 v59, 0xffff0000, v142
	v_pk_mul_f32 v[58:59], v[6:7], v[58:59]
	v_cvt_pk_bf16_f32 v54, v58, v59
	v_lshlrev_b32_e32 v56, 16, v139
	v_and_b32_e32 v57, 0xffff0000, v139
	v_pk_fma_f32 v[0:1], v[0:1], v[134:135], v[56:57]
	v_lshlrev_b32_e32 v58, 16, v143
	v_and_b32_e32 v59, 0xffff0000, v143
	v_pk_mul_f32 v[58:59], v[0:1], v[58:59]
	v_cvt_pk_bf16_f32 v55, v58, v59
	global_store_dwordx4 v[78:79], v[52:55], off offset:-2048
	s_waitcnt vmcnt(3)
	v_lshlrev_b32_e32 v56, 16, v152
	v_and_b32_e32 v57, 0xffff0000, v152
	v_pk_fma_f32 v[30:31], v[30:31], v[144:145], v[56:57]
	v_lshlrev_b32_e32 v58, 16, v156
	v_and_b32_e32 v59, 0xffff0000, v156
	v_pk_mul_f32 v[58:59], v[30:31], v[58:59]
	v_cvt_pk_bf16_f32 v12, v58, v59
	v_lshlrev_b32_e32 v56, 16, v153
	v_and_b32_e32 v57, 0xffff0000, v153
	v_pk_fma_f32 v[4:5], v[4:5], v[146:147], v[56:57]
	v_lshlrev_b32_e32 v58, 16, v157
	v_and_b32_e32 v59, 0xffff0000, v157
	v_pk_mul_f32 v[58:59], v[4:5], v[58:59]
	v_cvt_pk_bf16_f32 v13, v58, v59
	v_lshlrev_b32_e32 v56, 16, v154
	v_and_b32_e32 v57, 0xffff0000, v154
	v_pk_fma_f32 v[6:7], v[6:7], v[148:149], v[56:57]
	v_lshlrev_b32_e32 v58, 16, v158
	v_and_b32_e32 v59, 0xffff0000, v158
	v_pk_mul_f32 v[58:59], v[6:7], v[58:59]
	v_cvt_pk_bf16_f32 v14, v58, v59
	v_lshlrev_b32_e32 v56, 16, v155
	v_and_b32_e32 v57, 0xffff0000, v155
	v_pk_fma_f32 v[0:1], v[0:1], v[150:151], v[56:57]
	v_lshlrev_b32_e32 v58, 16, v159
	v_and_b32_e32 v59, 0xffff0000, v159
	v_pk_mul_f32 v[58:59], v[0:1], v[58:59]
	v_cvt_pk_bf16_f32 v15, v58, v59
	global_store_dwordx4 v[78:79], v[12:15], off
	s_waitcnt vmcnt(2)
	v_lshlrev_b32_e32 v56, 16, v168
	v_and_b32_e32 v57, 0xffff0000, v168
	v_pk_fma_f32 v[30:31], v[30:31], v[160:161], v[56:57]
	v_lshlrev_b32_e32 v58, 16, v172
	v_and_b32_e32 v59, 0xffff0000, v172
	v_pk_mul_f32 v[58:59], v[30:31], v[58:59]
	v_cvt_pk_bf16_f32 v52, v58, v59
	v_lshlrev_b32_e32 v56, 16, v169
	v_and_b32_e32 v57, 0xffff0000, v169
	v_pk_fma_f32 v[4:5], v[4:5], v[162:163], v[56:57]
	v_lshlrev_b32_e32 v58, 16, v173
	v_and_b32_e32 v59, 0xffff0000, v173
	v_pk_mul_f32 v[58:59], v[4:5], v[58:59]
	v_cvt_pk_bf16_f32 v53, v58, v59
	v_lshlrev_b32_e32 v56, 16, v170
	v_and_b32_e32 v57, 0xffff0000, v170
	v_pk_fma_f32 v[6:7], v[6:7], v[164:165], v[56:57]
	v_lshlrev_b32_e32 v58, 16, v174
	v_and_b32_e32 v59, 0xffff0000, v174
	v_pk_mul_f32 v[58:59], v[6:7], v[58:59]
	v_cvt_pk_bf16_f32 v54, v58, v59
	v_lshlrev_b32_e32 v56, 16, v171
	v_and_b32_e32 v57, 0xffff0000, v171
	v_pk_fma_f32 v[0:1], v[0:1], v[166:167], v[56:57]
	v_lshlrev_b32_e32 v58, 16, v175
	v_and_b32_e32 v59, 0xffff0000, v175
	v_pk_mul_f32 v[58:59], v[0:1], v[58:59]
	v_cvt_pk_bf16_f32 v55, v58, v59
	global_store_dwordx4 v[78:79], v[52:55], off offset:2048
	s_waitcnt vmcnt(1)
	v_lshlrev_b32_e32 v56, 16, v40
	v_and_b32_e32 v57, 0xffff0000, v40
	v_pk_fma_f32 v[30:31], v[30:31], v[32:33], v[56:57]
	v_lshlrev_b32_e32 v58, 16, v44
	v_and_b32_e32 v59, 0xffff0000, v44
	v_pk_mul_f32 v[58:59], v[30:31], v[58:59]
	v_cvt_pk_bf16_f32 v12, v58, v59
	v_lshlrev_b32_e32 v56, 16, v41
	v_and_b32_e32 v57, 0xffff0000, v41
	v_pk_fma_f32 v[4:5], v[4:5], v[34:35], v[56:57]
	v_lshlrev_b32_e32 v58, 16, v45
	v_and_b32_e32 v59, 0xffff0000, v45
	v_pk_mul_f32 v[58:59], v[4:5], v[58:59]
	v_cvt_pk_bf16_f32 v13, v58, v59
	v_lshlrev_b32_e32 v56, 16, v42
	v_and_b32_e32 v57, 0xffff0000, v42
	v_pk_fma_f32 v[6:7], v[6:7], v[36:37], v[56:57]
	v_lshlrev_b32_e32 v58, 16, v46
	v_and_b32_e32 v59, 0xffff0000, v46
	v_pk_mul_f32 v[58:59], v[6:7], v[58:59]
	v_cvt_pk_bf16_f32 v14, v58, v59
	v_lshlrev_b32_e32 v56, 16, v43
	v_and_b32_e32 v57, 0xffff0000, v43
	v_pk_fma_f32 v[0:1], v[0:1], v[38:39], v[56:57]
	v_lshlrev_b32_e32 v58, 16, v47
	v_and_b32_e32 v59, 0xffff0000, v47
	v_pk_mul_f32 v[58:59], v[0:1], v[58:59]
	v_cvt_pk_bf16_f32 v15, v58, v59
	global_store_dwordx4 v[28:29], v[12:15], off offset:-2048
	s_waitcnt vmcnt(0)
	v_lshlrev_b32_e32 v56, 16, v68
	v_and_b32_e32 v57, 0xffff0000, v68
	v_pk_fma_f32 v[30:31], v[30:31], v[60:61], v[56:57]
	v_lshlrev_b32_e32 v58, 16, v72
	v_and_b32_e32 v59, 0xffff0000, v72
	v_pk_mul_f32 v[58:59], v[30:31], v[58:59]
	v_cvt_pk_bf16_f32 v52, v58, v59
	v_lshlrev_b32_e32 v56, 16, v69
	v_and_b32_e32 v57, 0xffff0000, v69
	v_pk_fma_f32 v[4:5], v[4:5], v[62:63], v[56:57]
	v_lshlrev_b32_e32 v58, 16, v73
	v_and_b32_e32 v59, 0xffff0000, v73
	v_pk_mul_f32 v[58:59], v[4:5], v[58:59]
	v_cvt_pk_bf16_f32 v53, v58, v59
	v_lshlrev_b32_e32 v56, 16, v70
	v_and_b32_e32 v57, 0xffff0000, v70
	v_pk_fma_f32 v[6:7], v[6:7], v[64:65], v[56:57]
	v_lshlrev_b32_e32 v58, 16, v74
	v_and_b32_e32 v59, 0xffff0000, v74
	v_pk_mul_f32 v[58:59], v[6:7], v[58:59]
	v_cvt_pk_bf16_f32 v54, v58, v59
	v_lshlrev_b32_e32 v56, 16, v71
	v_and_b32_e32 v57, 0xffff0000, v71
	v_pk_fma_f32 v[0:1], v[0:1], v[66:67], v[56:57]
	v_lshlrev_b32_e32 v58, 16, v75
	v_and_b32_e32 v59, 0xffff0000, v75
	v_pk_mul_f32 v[58:59], v[0:1], v[58:59]
	v_cvt_pk_bf16_f32 v55, v58, v59
	global_store_dwordx4 v[28:29], v[52:55], off
	s_add_i32 s2, s2, -8
	s_cmp_eq_u32 s2, 0
	s_cbranch_scc0 .LBB0_1527
	v_readlane_b32 s2, v254, 0
	v_readlane_b32 s3, v254, 1
	s_add_i32 s16, s16, s2
	v_readlane_b32 s2, v255, 28
	v_readlane_b32 s3, v255, 29
	s_cmpk_gt_i32 s16, 0xff
	s_nop 0
	v_lshl_add_u64 v[22:23], v[22:23], 0, s[2:3]
	v_readlane_b32 s2, v254, 13
	v_readlane_b32 s3, v254, 14
	s_nop 1
	v_lshl_add_u64 v[24:25], v[24:25], 0, s[2:3]
	v_readlane_b32 s2, v254, 11
	v_readlane_b32 s3, v254, 12
	s_nop 1
	v_lshl_add_u64 v[26:27], v[26:27], 0, s[2:3]
	s_cbranch_scc0 .LBB0_1512
